# P8 SwiGLU epilogue rewritten with packed f32 multiplies/adds (36 instead of 52 VALU per 8 outputs, same operations and rounding)
# speedup vs baseline: 1.0050x; 1.0050x over previous
; __device__ __forceinline__ unsigned cvt_pk_bf16(float lo, float hi) { unsigned r; asm volatile("v_cvt_pk_bf16_f32 %0, %1, %2" : "=v"(r) : "v"(lo), "v"(hi)); return r; }
; __device__ __forceinline__ float silu_f(float x) { return x * __builtin_amdgcn_rcpf(1.0f + __expf(-x)); }
;     __device__ __forceinline__ void operator()(const f32x4 (&acc)[2][2][4][2], const Unit& u, int wr, int wc, int fr, int fq) const {
;         const int row0 = u.pm * BM + wr * 64 + fr, col0 = u.pn * HALF + wc * 32 + 8 * fq;
; #pragma unroll
;         for (int ai = 0; ai < 2; ++ai)
; #pragma unroll
;             for (int m = 0; m < 4; ++m) {
;                 float r[8];
; #pragma unroll
;                 for (int n = 0; n < 2; ++n)
; #pragma unroll
;                     for (int j = 0; j < 4; ++j) r[n * 4 + j] = silu_f(acc[ai][0][m][n][j]) * acc[ai][1][m][n][j];
;                 u32x4 w; w.x = cvt_pk_bf16(r[0], r[1]); w.y = cvt_pk_bf16(r[2], r[3]); w.z = cvt_pk_bf16(r[4], r[5]); w.w = cvt_pk_bf16(r[6], r[7]);
;                 *(u32x4*)(O + (size_t)(row0 + ai * HALF + m * 16) * 2816 + col0) = w;
;             }
;     }
.LBB0_1178:
	s_mov_b32 s0, 0xbfb8aa3b
	v_mov_b32_e32 v154, s0
	v_mov_b32_e32 v155, s0
	v_lshl_add_u32 v151, s38, 8, v1
	v_lshl_or_b32 v152, s52, 7, v147
	v_ashrrev_i32_e32 v153, 31, v152
	v_mov_b64_e32 v[156:157], s[8:9]
	v_mad_i64_i32 v[156:157], s[0:1], v151, s51, v[156:157]
	v_lshlrev_b64 v[152:153], 1, v[152:153]
	v_lshl_add_u64 v[156:157], v[156:157], 0, v[152:153]
	s_mov_b32 s1, 0
	v_pk_mul_f32 v[160:161], v[126:127], v[154:155]
	v_pk_mul_f32 v[162:163], v[128:129], v[154:155]
	v_pk_mul_f32 v[164:165], v[122:123], v[154:155]
	v_pk_mul_f32 v[166:167], v[124:125], v[154:155]
	v_exp_f32_e32 v160, v160
	v_exp_f32_e32 v161, v161
	v_exp_f32_e32 v162, v162
	v_exp_f32_e32 v163, v163
	v_exp_f32_e32 v164, v164
	v_exp_f32_e32 v165, v165
	v_exp_f32_e32 v166, v166
	v_exp_f32_e32 v167, v167
	v_pk_add_f32 v[160:161], v[160:161], 1.0 op_sel_hi:[1,0]
	v_pk_add_f32 v[162:163], v[162:163], 1.0 op_sel_hi:[1,0]
	v_pk_add_f32 v[164:165], v[164:165], 1.0 op_sel_hi:[1,0]
	v_pk_add_f32 v[166:167], v[166:167], 1.0 op_sel_hi:[1,0]
	v_rcp_f32_e32 v160, v160
	v_rcp_f32_e32 v161, v161
	v_rcp_f32_e32 v162, v162
	v_rcp_f32_e32 v163, v163
	v_rcp_f32_e32 v164, v164
	v_rcp_f32_e32 v165, v165
	v_rcp_f32_e32 v166, v166
	v_rcp_f32_e32 v167, v167
	v_pk_mul_f32 v[126:127], v[126:127], v[160:161]
	v_pk_mul_f32 v[128:129], v[128:129], v[162:163]
	v_pk_mul_f32 v[122:123], v[122:123], v[164:165]
	v_pk_mul_f32 v[124:125], v[124:125], v[166:167]
	v_pk_mul_f32 v[126:127], v[126:127], v[118:119]
	v_pk_mul_f32 v[128:129], v[128:129], v[120:121]
	v_pk_mul_f32 v[122:123], v[122:123], v[114:115]
	v_pk_mul_f32 v[124:125], v[124:125], v[116:117]
	v_cvt_pk_bf16_f32 v118, v126, v127
	v_cvt_pk_bf16_f32 v119, v128, v129
	v_cvt_pk_bf16_f32 v120, v122, v123
	v_cvt_pk_bf16_f32 v121, v124, v125
	global_store_dwordx4 v[156:157], v[118:121], off sc1
	s_mov_b32 s0, 0x16000
	v_lshl_add_u64 v[156:157], v[156:157], 0, s[0:1]
	v_pk_mul_f32 v[160:161], v[110:111], v[154:155]
	v_pk_mul_f32 v[162:163], v[112:113], v[154:155]
	v_pk_mul_f32 v[164:165], v[106:107], v[154:155]
	v_pk_mul_f32 v[166:167], v[108:109], v[154:155]
	v_exp_f32_e32 v160, v160
	v_exp_f32_e32 v161, v161
	v_exp_f32_e32 v162, v162
	v_exp_f32_e32 v163, v163
	v_exp_f32_e32 v164, v164
	v_exp_f32_e32 v165, v165
	v_exp_f32_e32 v166, v166
	v_exp_f32_e32 v167, v167
	v_pk_add_f32 v[160:161], v[160:161], 1.0 op_sel_hi:[1,0]
	v_pk_add_f32 v[162:163], v[162:163], 1.0 op_sel_hi:[1,0]
	v_pk_add_f32 v[164:165], v[164:165], 1.0 op_sel_hi:[1,0]
	v_pk_add_f32 v[166:167], v[166:167], 1.0 op_sel_hi:[1,0]
	v_rcp_f32_e32 v160, v160
	v_rcp_f32_e32 v161, v161
	v_rcp_f32_e32 v162, v162
	v_rcp_f32_e32 v163, v163
	v_rcp_f32_e32 v164, v164
	v_rcp_f32_e32 v165, v165
	v_rcp_f32_e32 v166, v166
	v_rcp_f32_e32 v167, v167
	v_pk_mul_f32 v[110:111], v[110:111], v[160:161]
	v_pk_mul_f32 v[112:113], v[112:113], v[162:163]
	v_pk_mul_f32 v[106:107], v[106:107], v[164:165]
	v_pk_mul_f32 v[108:109], v[108:109], v[166:167]
	v_pk_mul_f32 v[110:111], v[110:111], v[102:103]
	v_pk_mul_f32 v[112:113], v[112:113], v[104:105]
	v_pk_mul_f32 v[106:107], v[106:107], v[98:99]
	v_pk_mul_f32 v[108:109], v[108:109], v[100:101]
	v_cvt_pk_bf16_f32 v102, v110, v111
	v_cvt_pk_bf16_f32 v103, v112, v113
	v_cvt_pk_bf16_f32 v104, v106, v107
	v_cvt_pk_bf16_f32 v105, v108, v109
	global_store_dwordx4 v[156:157], v[102:105], off sc1
	s_mov_b32 s0, 0x16000
	v_lshl_add_u64 v[156:157], v[156:157], 0, s[0:1]
	v_pk_mul_f32 v[160:161], v[94:95], v[154:155]
	v_pk_mul_f32 v[162:163], v[96:97], v[154:155]
	v_pk_mul_f32 v[164:165], v[90:91], v[154:155]
	v_pk_mul_f32 v[166:167], v[92:93], v[154:155]
	v_exp_f32_e32 v160, v160
	v_exp_f32_e32 v161, v161
	v_exp_f32_e32 v162, v162
	v_exp_f32_e32 v163, v163
	v_exp_f32_e32 v164, v164
	v_exp_f32_e32 v165, v165
	v_exp_f32_e32 v166, v166
	v_exp_f32_e32 v167, v167
	v_pk_add_f32 v[160:161], v[160:161], 1.0 op_sel_hi:[1,0]
	v_pk_add_f32 v[162:163], v[162:163], 1.0 op_sel_hi:[1,0]
	v_pk_add_f32 v[164:165], v[164:165], 1.0 op_sel_hi:[1,0]
	v_pk_add_f32 v[166:167], v[166:167], 1.0 op_sel_hi:[1,0]
	v_rcp_f32_e32 v160, v160
	v_rcp_f32_e32 v161, v161
	v_rcp_f32_e32 v162, v162
	v_rcp_f32_e32 v163, v163
	v_rcp_f32_e32 v164, v164
	v_rcp_f32_e32 v165, v165
	v_rcp_f32_e32 v166, v166
	v_rcp_f32_e32 v167, v167
	v_pk_mul_f32 v[94:95], v[94:95], v[160:161]
	v_pk_mul_f32 v[96:97], v[96:97], v[162:163]
	v_pk_mul_f32 v[90:91], v[90:91], v[164:165]
	v_pk_mul_f32 v[92:93], v[92:93], v[166:167]
	v_pk_mul_f32 v[94:95], v[94:95], v[86:87]
	v_pk_mul_f32 v[96:97], v[96:97], v[88:89]
	v_pk_mul_f32 v[90:91], v[90:91], v[82:83]
	v_pk_mul_f32 v[92:93], v[92:93], v[84:85]
	v_cvt_pk_bf16_f32 v86, v94, v95
	v_cvt_pk_bf16_f32 v87, v96, v97
	v_cvt_pk_bf16_f32 v88, v90, v91
	v_cvt_pk_bf16_f32 v89, v92, v93
	global_store_dwordx4 v[156:157], v[86:89], off sc1
	s_mov_b32 s0, 0x16000
	v_lshl_add_u64 v[156:157], v[156:157], 0, s[0:1]
	v_pk_mul_f32 v[160:161], v[78:79], v[154:155]
	v_pk_mul_f32 v[162:163], v[80:81], v[154:155]
	v_pk_mul_f32 v[164:165], v[74:75], v[154:155]
	v_pk_mul_f32 v[166:167], v[76:77], v[154:155]
	v_exp_f32_e32 v160, v160
	v_exp_f32_e32 v161, v161
	v_exp_f32_e32 v162, v162
	v_exp_f32_e32 v163, v163
	v_exp_f32_e32 v164, v164
	v_exp_f32_e32 v165, v165
	v_exp_f32_e32 v166, v166
	v_exp_f32_e32 v167, v167
	v_pk_add_f32 v[160:161], v[160:161], 1.0 op_sel_hi:[1,0]
	v_pk_add_f32 v[162:163], v[162:163], 1.0 op_sel_hi:[1,0]
	v_pk_add_f32 v[164:165], v[164:165], 1.0 op_sel_hi:[1,0]
	v_pk_add_f32 v[166:167], v[166:167], 1.0 op_sel_hi:[1,0]
	v_rcp_f32_e32 v160, v160
	v_rcp_f32_e32 v161, v161
	v_rcp_f32_e32 v162, v162
	v_rcp_f32_e32 v163, v163
	v_rcp_f32_e32 v164, v164
	v_rcp_f32_e32 v165, v165
; __device__ __forceinline__ unsigned cvt_pk_bf16(float lo, float hi) { unsigned r; asm volatile("v_cvt_pk_bf16_f32 %0, %1, %2" : "=v"(r) : "v"(lo), "v"(hi)); return r; }
; __device__ __forceinline__ float silu_f(float x) { return x * __builtin_amdgcn_rcpf(1.0f + __expf(-x)); }
;     __device__ __forceinline__ void operator()(const f32x4 (&acc)[2][2][4][2], const Unit& u, int wr, int wc, int fr, int fq) const {
;         const int row0 = u.pm * BM + wr * 64 + fr, col0 = u.pn * HALF + wc * 32 + 8 * fq;
; #pragma unroll
;         for (int ai = 0; ai < 2; ++ai)
; #pragma unroll
;             for (int m = 0; m < 4; ++m) {
;                 float r[8];
; #pragma unroll
;                 for (int n = 0; n < 2; ++n)
; #pragma unroll
;                     for (int j = 0; j < 4; ++j) r[n * 4 + j] = silu_f(acc[ai][0][m][n][j]) * acc[ai][1][m][n][j];
;                 u32x4 w; w.x = cvt_pk_bf16(r[0], r[1]); w.y = cvt_pk_bf16(r[2], r[3]); w.z = cvt_pk_bf16(r[4], r[5]); w.w = cvt_pk_bf16(r[6], r[7]);
;                 *(u32x4*)(O + (size_t)(row0 + ai * HALF + m * 16) * 2816 + col0) = w;
;             }
;     }
	v_rcp_f32_e32 v166, v166
	v_rcp_f32_e32 v167, v167
	v_pk_mul_f32 v[78:79], v[78:79], v[160:161]
	v_pk_mul_f32 v[80:81], v[80:81], v[162:163]
	v_pk_mul_f32 v[74:75], v[74:75], v[164:165]
	v_pk_mul_f32 v[76:77], v[76:77], v[166:167]
	v_pk_mul_f32 v[78:79], v[78:79], v[70:71]
	v_pk_mul_f32 v[80:81], v[80:81], v[72:73]
	v_pk_mul_f32 v[74:75], v[74:75], v[66:67]
	v_pk_mul_f32 v[76:77], v[76:77], v[68:69]
	v_cvt_pk_bf16_f32 v70, v78, v79
	v_cvt_pk_bf16_f32 v71, v80, v81
	v_cvt_pk_bf16_f32 v72, v74, v75
	v_cvt_pk_bf16_f32 v73, v76, v77
	global_store_dwordx4 v[156:157], v[70:73], off sc1
	s_mov_b32 s0, 0x6e000
	v_lshl_add_u64 v[156:157], v[156:157], 0, s[0:1]
	v_pk_mul_f32 v[160:161], v[62:63], v[154:155]
	v_pk_mul_f32 v[162:163], v[64:65], v[154:155]
	v_pk_mul_f32 v[164:165], v[58:59], v[154:155]
	v_pk_mul_f32 v[166:167], v[60:61], v[154:155]
	v_exp_f32_e32 v160, v160
	v_exp_f32_e32 v161, v161
	v_exp_f32_e32 v162, v162
	v_exp_f32_e32 v163, v163
	v_exp_f32_e32 v164, v164
	v_exp_f32_e32 v165, v165
	v_exp_f32_e32 v166, v166
	v_exp_f32_e32 v167, v167
	v_pk_add_f32 v[160:161], v[160:161], 1.0 op_sel_hi:[1,0]
	v_pk_add_f32 v[162:163], v[162:163], 1.0 op_sel_hi:[1,0]
	v_pk_add_f32 v[164:165], v[164:165], 1.0 op_sel_hi:[1,0]
	v_pk_add_f32 v[166:167], v[166:167], 1.0 op_sel_hi:[1,0]
	v_rcp_f32_e32 v160, v160
	v_rcp_f32_e32 v161, v161
	v_rcp_f32_e32 v162, v162
	v_rcp_f32_e32 v163, v163
	v_rcp_f32_e32 v164, v164
	v_rcp_f32_e32 v165, v165
	v_rcp_f32_e32 v166, v166
	v_rcp_f32_e32 v167, v167
	v_pk_mul_f32 v[62:63], v[62:63], v[160:161]
	v_pk_mul_f32 v[64:65], v[64:65], v[162:163]
	v_pk_mul_f32 v[58:59], v[58:59], v[164:165]
	v_pk_mul_f32 v[60:61], v[60:61], v[166:167]
	v_pk_mul_f32 v[62:63], v[62:63], v[54:55]
	v_pk_mul_f32 v[64:65], v[64:65], v[56:57]
	v_pk_mul_f32 v[58:59], v[58:59], v[50:51]
	v_pk_mul_f32 v[60:61], v[60:61], v[52:53]
	v_cvt_pk_bf16_f32 v54, v62, v63
	v_cvt_pk_bf16_f32 v55, v64, v65
	v_cvt_pk_bf16_f32 v56, v58, v59
	v_cvt_pk_bf16_f32 v57, v60, v61
	global_store_dwordx4 v[156:157], v[54:57], off sc1
	s_mov_b32 s0, 0x16000
	v_lshl_add_u64 v[156:157], v[156:157], 0, s[0:1]
	v_pk_mul_f32 v[160:161], v[46:47], v[154:155]
	v_pk_mul_f32 v[162:163], v[48:49], v[154:155]
	v_pk_mul_f32 v[164:165], v[42:43], v[154:155]
	v_pk_mul_f32 v[166:167], v[44:45], v[154:155]
	v_exp_f32_e32 v160, v160
	v_exp_f32_e32 v161, v161
	v_exp_f32_e32 v162, v162
	v_exp_f32_e32 v163, v163
	v_exp_f32_e32 v164, v164
	v_exp_f32_e32 v165, v165
	v_exp_f32_e32 v166, v166
	v_exp_f32_e32 v167, v167
	v_pk_add_f32 v[160:161], v[160:161], 1.0 op_sel_hi:[1,0]
	v_pk_add_f32 v[162:163], v[162:163], 1.0 op_sel_hi:[1,0]
	v_pk_add_f32 v[164:165], v[164:165], 1.0 op_sel_hi:[1,0]
	v_pk_add_f32 v[166:167], v[166:167], 1.0 op_sel_hi:[1,0]
	v_rcp_f32_e32 v160, v160
	v_rcp_f32_e32 v161, v161
	v_rcp_f32_e32 v162, v162
	v_rcp_f32_e32 v163, v163
	v_rcp_f32_e32 v164, v164
	v_rcp_f32_e32 v165, v165
	v_rcp_f32_e32 v166, v166
	v_rcp_f32_e32 v167, v167
	v_pk_mul_f32 v[46:47], v[46:47], v[160:161]
	v_pk_mul_f32 v[48:49], v[48:49], v[162:163]
	v_pk_mul_f32 v[42:43], v[42:43], v[164:165]
	v_pk_mul_f32 v[44:45], v[44:45], v[166:167]
	v_pk_mul_f32 v[46:47], v[46:47], v[38:39]
	v_pk_mul_f32 v[48:49], v[48:49], v[40:41]
	v_pk_mul_f32 v[42:43], v[42:43], v[34:35]
	v_pk_mul_f32 v[44:45], v[44:45], v[36:37]
	v_cvt_pk_bf16_f32 v38, v46, v47
	v_cvt_pk_bf16_f32 v39, v48, v49
	v_cvt_pk_bf16_f32 v40, v42, v43
	v_cvt_pk_bf16_f32 v41, v44, v45
	global_store_dwordx4 v[156:157], v[38:41], off sc1
	s_mov_b32 s0, 0x16000
	v_lshl_add_u64 v[156:157], v[156:157], 0, s[0:1]
	v_pk_mul_f32 v[160:161], v[30:31], v[154:155]
	v_pk_mul_f32 v[162:163], v[32:33], v[154:155]
	v_pk_mul_f32 v[164:165], v[26:27], v[154:155]
	v_pk_mul_f32 v[166:167], v[28:29], v[154:155]
	v_exp_f32_e32 v160, v160
	v_exp_f32_e32 v161, v161
	v_exp_f32_e32 v162, v162
	v_exp_f32_e32 v163, v163
	v_exp_f32_e32 v164, v164
	v_exp_f32_e32 v165, v165
	v_exp_f32_e32 v166, v166
	v_exp_f32_e32 v167, v167
	v_pk_add_f32 v[160:161], v[160:161], 1.0 op_sel_hi:[1,0]
	v_pk_add_f32 v[162:163], v[162:163], 1.0 op_sel_hi:[1,0]
	v_pk_add_f32 v[164:165], v[164:165], 1.0 op_sel_hi:[1,0]
	v_pk_add_f32 v[166:167], v[166:167], 1.0 op_sel_hi:[1,0]
	v_rcp_f32_e32 v160, v160
	v_rcp_f32_e32 v161, v161
	v_rcp_f32_e32 v162, v162
	v_rcp_f32_e32 v163, v163
	v_rcp_f32_e32 v164, v164
	v_rcp_f32_e32 v165, v165
	v_rcp_f32_e32 v166, v166
	v_rcp_f32_e32 v167, v167
	v_pk_mul_f32 v[30:31], v[30:31], v[160:161]
	v_pk_mul_f32 v[32:33], v[32:33], v[162:163]
	v_pk_mul_f32 v[26:27], v[26:27], v[164:165]
	v_pk_mul_f32 v[28:29], v[28:29], v[166:167]
	v_pk_mul_f32 v[30:31], v[30:31], v[22:23]
	v_pk_mul_f32 v[32:33], v[32:33], v[24:25]
	v_pk_mul_f32 v[26:27], v[26:27], v[18:19]
	v_pk_mul_f32 v[28:29], v[28:29], v[20:21]
	v_cvt_pk_bf16_f32 v22, v30, v31
	v_cvt_pk_bf16_f32 v23, v32, v33
	v_cvt_pk_bf16_f32 v24, v26, v27
	v_cvt_pk_bf16_f32 v25, v28, v29
	global_store_dwordx4 v[156:157], v[22:25], off sc1
	s_mov_b32 s0, 0x16000
	v_lshl_add_u64 v[156:157], v[156:157], 0, s[0:1]
	v_pk_mul_f32 v[160:161], v[14:15], v[154:155]
	v_pk_mul_f32 v[162:163], v[16:17], v[154:155]
	v_pk_mul_f32 v[164:165], v[10:11], v[154:155]
	v_pk_mul_f32 v[166:167], v[12:13], v[154:155]
	v_exp_f32_e32 v160, v160
	v_exp_f32_e32 v161, v161
	v_exp_f32_e32 v162, v162
	v_exp_f32_e32 v163, v163
	v_exp_f32_e32 v164, v164
	v_exp_f32_e32 v165, v165
	v_exp_f32_e32 v166, v166
	v_exp_f32_e32 v167, v167
	v_pk_add_f32 v[160:161], v[160:161], 1.0 op_sel_hi:[1,0]
	v_pk_add_f32 v[162:163], v[162:163], 1.0 op_sel_hi:[1,0]
	v_pk_add_f32 v[164:165], v[164:165], 1.0 op_sel_hi:[1,0]
	v_pk_add_f32 v[166:167], v[166:167], 1.0 op_sel_hi:[1,0]
	v_rcp_f32_e32 v160, v160
	v_rcp_f32_e32 v161, v161
	v_rcp_f32_e32 v162, v162
	v_rcp_f32_e32 v163, v163
	v_rcp_f32_e32 v164, v164
	v_rcp_f32_e32 v165, v165
	v_rcp_f32_e32 v166, v166
	v_rcp_f32_e32 v167, v167
	v_pk_mul_f32 v[14:15], v[14:15], v[160:161]
	v_pk_mul_f32 v[16:17], v[16:17], v[162:163]
	v_pk_mul_f32 v[10:11], v[10:11], v[164:165]
	v_pk_mul_f32 v[12:13], v[12:13], v[166:167]
	v_pk_mul_f32 v[14:15], v[14:15], v[6:7]
	v_pk_mul_f32 v[16:17], v[16:17], v[8:9]
	v_pk_mul_f32 v[10:11], v[10:11], v[2:3]
	v_pk_mul_f32 v[12:13], v[12:13], v[4:5]
	v_cvt_pk_bf16_f32 v6, v14, v15
	v_cvt_pk_bf16_f32 v7, v16, v17
	v_cvt_pk_bf16_f32 v8, v10, v11
	v_cvt_pk_bf16_f32 v9, v12, v13
	global_store_dwordx4 v[156:157], v[6:9], off sc1
	s_andn2_b64 vcc, exec, s[4:5]
	s_mov_b64 s[0:1], -1
	s_cbranch_vccnz .LBB0_1171
	s_andn2_b64 vcc, exec, s[10:11]
	s_cbranch_vccnz .LBB0_1170
	s_barrier
	s_branch .LBB0_1170
